# v28 + grid barrier polls the release word with a returning atomic add of 0 instead of a device-scope load
# baseline (speedup 1.0000x reference)
; __device__ __forceinline__ unsigned xb_ld(unsigned* p)              { return __hip_atomic_load(p, __ATOMIC_RELAXED, __HIP_MEMORY_SCOPE_AGENT); }
; __device__ __forceinline__ unsigned xb_add(unsigned* p, unsigned v) { return __hip_atomic_fetch_add(p, v, __ATOMIC_RELAXED, __HIP_MEMORY_SCOPE_AGENT); }
; #define XB_SPIN(cond, bar) do { unsigned _sp = 0; while (cond) { __builtin_amdgcn_s_sleep(1); \
;     if ((++_sp & 255u) == 0u) { if (xb_ld(&(bar)[XB_TMO])) break; if (_sp > XB_SPIN_CAP) { atomicAdd(&(bar)[XB_TMO], 1u); break; } } } } while (0)
; __device__ __forceinline__ void xcd_barrier(const XcdBarrier& b, int wave) {
;     ...
;         const unsigned old = xb_add(&bar[XB_XSUB(b.x)], 1u);
;         const unsigned gen = old / nloc;
;         if (old + 1u == (gen + 1u) * nloc) {
;             __builtin_amdgcn_fence(__ATOMIC_RELEASE, "agent");
;             asm volatile("s_waitcnt vmcnt(0)" ::: "memory");
;             const unsigned og = xb_add(&bar[XB_TOP], 1u);
;             const unsigned tg = og / nx;
;             if (og + 1u == (tg + 1u) * nx) xb_add(&bar[XB_TOPGEN], 1u);
;             else XB_SPIN(xb_ld(&bar[XB_TOPGEN]) == tg, bar);
;             __builtin_amdgcn_fence(__ATOMIC_ACQUIRE, "agent");
;             xb_add(&bar[XB_XGEN(b.x)], 1u);
;             asm volatile("s_waitcnt vmcnt(0)" ::: "memory");
;         } else {
;             XB_SPIN(xb_ld(&bar[XB_XGEN(b.x)]) == gen, bar);
;             __builtin_amdgcn_fence(__ATOMIC_ACQUIRE, "agent");
;             asm volatile("s_waitcnt vmcnt(0)" ::: "memory");
;         }
.LBB0_1071:
	v_readlane_b32 s0, v253, 51
	v_readlane_b32 s1, v253, 52
	v_cvt_f32_u32_e32 v0, v3
	v_sub_u32_e32 v5, 0, v3
	v_rcp_iflag_f32_e32 v0, v0
	s_nop 1
	global_atomic_add v4, v1, v224, s[0:1] sc0
	v_mul_f32_e32 v0, 0x4f7ffffe, v0
	v_cvt_u32_f32_e32 v0, v0
	v_mul_lo_u32 v5, v5, v0
	v_mul_hi_u32 v5, v0, v5
	v_add_u32_e32 v0, v0, v5
	s_waitcnt vmcnt(0)
	v_mul_hi_u32 v0, v4, v0
	v_mul_lo_u32 v5, v0, v3
	v_sub_u32_e32 v5, v4, v5
	v_add_u32_e32 v6, 1, v0
	v_cmp_ge_u32_e32 vcc, v5, v3
	v_add_u32_e32 v4, 1, v4
	s_nop 0
	v_cndmask_b32_e32 v0, v0, v6, vcc
	v_sub_u32_e32 v6, v5, v3
	v_cndmask_b32_e32 v5, v5, v6, vcc
	v_add_u32_e32 v6, 1, v0
	v_cmp_ge_u32_e32 vcc, v5, v3
	s_nop 1
	v_cndmask_b32_e32 v0, v0, v6, vcc
	v_mul_lo_u32 v5, v3, v0
	v_add_u32_e32 v3, v5, v3
	v_cmp_ne_u32_e32 vcc, v4, v3
	s_and_saveexec_b64 s[0:1], vcc
	s_xor_b64 s[22:23], exec, s[0:1]
	s_cbranch_execz .LBB0_1085
	v_readlane_b32 s0, v253, 53
	v_readlane_b32 s1, v253, 54
	s_waitcnt lgkmcnt(0)
	s_nop 3
	global_atomic_add v2, v1, v1, s[0:1] sc0
	s_waitcnt vmcnt(0)
	v_cmp_eq_u32_e32 vcc, v2, v0
	s_and_saveexec_b64 s[24:25], vcc
	s_cbranch_execz .LBB0_1084
	s_mov_b32 s2, 1
	s_mov_b64 s[0:1], 0
	s_branch .LBB0_1075

; __device__ __forceinline__ unsigned xb_ld(unsigned* p)              { return __hip_atomic_load(p, __ATOMIC_RELAXED, __HIP_MEMORY_SCOPE_AGENT); }
; #define XB_SPIN(cond, bar) do { unsigned _sp = 0; while (cond) { __builtin_amdgcn_s_sleep(1); \
;     if ((++_sp & 255u) == 0u) { if (xb_ld(&(bar)[XB_TMO])) break; if (_sp > XB_SPIN_CAP) { atomicAdd(&(bar)[XB_TMO], 1u); break; } } } } while (0)
; __device__ __forceinline__ void xcd_barrier(const XcdBarrier& b, int wave) {
;     ...
;             XB_SPIN(xb_ld(&bar[XB_XGEN(b.x)]) == gen, bar);
.LBB0_1079:
	v_readlane_b32 s4, v253, 53
	v_readlane_b32 s5, v253, 54
	s_add_i32 s2, s2, 1
	s_mov_b64 s[38:39], -1
	s_nop 2
	global_atomic_add v2, v1, v1, s[4:5] sc0
	s_waitcnt vmcnt(0)
	v_cmp_ne_u32_e32 vcc, v2, v0
	s_orn2_b64 s[36:37], vcc, exec
	s_branch .LBB0_1074

; __device__ __forceinline__ unsigned xb_ld(unsigned* p)              { return __hip_atomic_load(p, __ATOMIC_RELAXED, __HIP_MEMORY_SCOPE_AGENT); }
; __device__ __forceinline__ unsigned xb_add(unsigned* p, unsigned v) { return __hip_atomic_fetch_add(p, v, __ATOMIC_RELAXED, __HIP_MEMORY_SCOPE_AGENT); }
; #define XB_SPIN(cond, bar) do { unsigned _sp = 0; while (cond) { __builtin_amdgcn_s_sleep(1); \
;     if ((++_sp & 255u) == 0u) { if (xb_ld(&(bar)[XB_TMO])) break; if (_sp > XB_SPIN_CAP) { atomicAdd(&(bar)[XB_TMO], 1u); break; } } } } while (0)
; __device__ __forceinline__ void xcd_barrier(const XcdBarrier& b, int wave) {
;     ...
;         const unsigned old = xb_add(&bar[XB_XSUB(b.x)], 1u);
;         const unsigned gen = old / nloc;
;         if (old + 1u == (gen + 1u) * nloc) {
;             __builtin_amdgcn_fence(__ATOMIC_RELEASE, "agent");
;             asm volatile("s_waitcnt vmcnt(0)" ::: "memory");
;             const unsigned og = xb_add(&bar[XB_TOP], 1u);
;             const unsigned tg = og / nx;
;             if (og + 1u == (tg + 1u) * nx) xb_add(&bar[XB_TOPGEN], 1u);
;             else XB_SPIN(xb_ld(&bar[XB_TOPGEN]) == tg, bar);
;             __builtin_amdgcn_fence(__ATOMIC_ACQUIRE, "agent");
;             xb_add(&bar[XB_XGEN(b.x)], 1u);
;             asm volatile("s_waitcnt vmcnt(0)" ::: "memory");
;         } else {
;             XB_SPIN(xb_ld(&bar[XB_XGEN(b.x)]) == gen, bar);
;             __builtin_amdgcn_fence(__ATOMIC_ACQUIRE, "agent");
;             asm volatile("s_waitcnt vmcnt(0)" ::: "memory");
;         }
.LBB0_1088:
	s_or_b64 exec, exec, s[22:23]
	s_waitcnt vmcnt(0)
	v_readfirstlane_b32 s0, v3
	v_sub_u32_e32 v4, 0, v2
	v_readlane_b32 s2, v253, 57
	v_add_u32_e32 v3, s0, v0
	v_cvt_f32_u32_e32 v0, v2
	v_readlane_b32 s3, v253, 58
	s_mov_b64 s[0:1], -1
	v_rcp_iflag_f32_e32 v0, v0
	s_nop 0
	v_mul_f32_e32 v0, 0x4f7ffffe, v0
	v_cvt_u32_f32_e32 v0, v0
	v_mul_lo_u32 v4, v4, v0
	v_mul_hi_u32 v4, v0, v4
	v_add_u32_e32 v0, v0, v4
	v_mul_hi_u32 v0, v3, v0
	v_mul_lo_u32 v4, v0, v2
	v_sub_u32_e32 v4, v3, v4
	v_cmp_ge_u32_e32 vcc, v4, v2
	v_add_u32_e32 v5, 1, v0
	v_add_u32_e32 v3, 1, v3
	v_cndmask_b32_e32 v0, v0, v5, vcc
	v_sub_u32_e32 v5, v4, v2
	v_cndmask_b32_e32 v4, v4, v5, vcc
	v_cmp_ge_u32_e32 vcc, v4, v2
	v_add_u32_e32 v4, 1, v0
	s_nop 0
	v_cndmask_b32_e32 v0, v0, v4, vcc
	v_mul_lo_u32 v4, v2, v0
	v_add_u32_e32 v2, v4, v2
	v_cmp_ne_u32_e32 vcc, v3, v2
	v_mov_b64_e32 v[2:3], s[2:3]
	s_and_saveexec_b64 s[22:23], vcc
	s_cbranch_execz .LBB0_1100
	v_readlane_b32 s0, v253, 53
	v_readlane_b32 s1, v253, 54
	s_nop 4
	global_atomic_add v2, v1, v1, s[0:1] sc0
	s_mov_b64 s[0:1], 0
	s_waitcnt vmcnt(0)
	v_cmp_eq_u32_e32 vcc, v2, v7
	s_and_saveexec_b64 s[24:25], vcc
	s_cbranch_execz .LBB0_1099
	s_mov_b32 s2, 1
	s_branch .LBB0_1092

; __device__ __forceinline__ unsigned xb_ld(unsigned* p)              { return __hip_atomic_load(p, __ATOMIC_RELAXED, __HIP_MEMORY_SCOPE_AGENT); }
; #define XB_SPIN(cond, bar) do { unsigned _sp = 0; while (cond) { __builtin_amdgcn_s_sleep(1); \
;     if ((++_sp & 255u) == 0u) { if (xb_ld(&(bar)[XB_TMO])) break; if (_sp > XB_SPIN_CAP) { atomicAdd(&(bar)[XB_TMO], 1u); break; } } } } while (0)
; __device__ __forceinline__ void xcd_barrier(const XcdBarrier& b, int wave) {
;     ...
;             XB_SPIN(xb_ld(&bar[XB_XGEN(b.x)]) == gen, bar);
.LBB0_1096:
	v_readlane_b32 s4, v253, 53
	v_readlane_b32 s5, v253, 54
	s_add_i32 s2, s2, 1
	s_mov_b64 s[38:39], -1
	s_nop 2
	global_atomic_add v2, v1, v1, s[4:5] sc0
	s_waitcnt vmcnt(0)
	v_cmp_ne_u32_e32 vcc, v2, v7
	s_orn2_b64 s[36:37], vcc, exec
	s_branch .LBB0_1091
